# grid barrier: the agent-scope L1 invalidate is issued by wave 1 right after the entry barrier (all loads drained, nothing loads through L1 before the closing barrier), overlapping the arrival/poll pat
# speedup vs baseline: 1.0149x; 1.0149x over previous
.LBB0_664:
	v_readlane_b32 s0, v254, 24
	v_readlane_b32 s1, v254, 25
	s_andn2_b64 vcc, exec, s[0:1]
	v_readlane_b32 s19, v254, 20
	s_cbranch_vccnz .LBB0_22
	s_waitcnt vmcnt(0)
	s_waitcnt vmcnt(0)
	s_barrier
	v_readfirstlane_b32 s0, v224
	s_cmp_eq_u32 s0, 64
	s_cbranch_scc0 .Lbi_skip
	s_mov_b64 s[2:3], exec
	s_mov_b64 exec, 1
	buffer_inv sc1
	s_waitcnt vmcnt(0)
	s_mov_b64 exec, s[2:3]
.Lbi_skip:
	s_mov_b64 s[2:3], exec
	v_readlane_b32 s0, v253, 3
	v_readlane_b32 s1, v253, 4
	s_and_b64 s[0:1], s[2:3], s[0:1]
	s_mov_b64 exec, s[0:1]
	s_cbranch_execz .LBB0_21
	s_add_i32 s8, 0, 0x24000
	v_mov_b32_e32 v0, s8
	s_waitcnt vmcnt(0) expcnt(0) lgkmcnt(0)
	ds_read_b32 v2, v0
	v_readlane_b32 s0, v254, 15
	s_waitcnt lgkmcnt(0)
	v_cmp_ne_u32_e32 vcc, 0, v2
	v_mov_b32_e32 v0, s0
	ds_read_b32 v0, v0
	s_cbranch_vccnz .LBB0_681
	s_mov_b32 s9, 1
	s_branch .LBB0_669

.LBB0_696:
	s_or_b64 exec, exec, s[4:5]
	s_waitcnt vmcnt(0)
	s_nop 0
	s_waitcnt vmcnt(0)

.LBB0_714:
	s_or_b64 exec, exec, s[0:1]
	s_mov_b64 s[0:1], exec
	v_mbcnt_lo_u32_b32 v0, s0, 0
	v_mbcnt_hi_u32_b32 v0, s1, v0
	v_cmp_eq_u32_e32 vcc, 0, v0
	s_waitcnt vmcnt(0)
	s_nop 0
	s_and_saveexec_b64 s[4:5], vcc
	s_cbranch_execz .LBB0_20
	s_bcnt1_i32_b64 s0, s[0:1]
	v_mov_b32_e32 v0, s0
	v_readlane_b32 s0, v254, 9
	v_readlane_b32 s1, v254, 10
	s_nop 4
	s_branch .LBB0_20
